# grid barrier: acquire-side L1 invalidate issued while waiting (no L1 fills possible until release), relay-word add removed
# speedup vs baseline: 1.0166x; 1.0108x over previous
.LBB0_91:
	s_or_b64 exec, exec, s[12:13]
	v_cvt_f32_u32_e32 v4, v2
	s_waitcnt vmcnt(0)
	v_readfirstlane_b32 s10, v3
	v_sub_u32_e32 v3, 0, v2
	v_rcp_iflag_f32_e32 v4, v4
	v_add_u32_e32 v5, s10, v1
	v_mul_f32_e32 v4, 0x4f7ffffe, v4
	v_cvt_u32_f32_e32 v4, v4
	v_mul_lo_u32 v1, v3, v4
	v_mul_hi_u32 v1, v4, v1
	v_add_u32_e32 v1, v4, v1
	v_mul_hi_u32 v1, v5, v1
	v_mul_lo_u32 v3, v1, v2
	v_sub_u32_e32 v3, v5, v3
	v_add_u32_e32 v4, 1, v1
	v_cmp_ge_u32_e32 vcc, v3, v2
	s_nop 1
	v_cndmask_b32_e32 v1, v1, v4, vcc
	v_sub_u32_e32 v4, v3, v2
	v_cndmask_b32_e32 v3, v3, v4, vcc
	v_add_u32_e32 v4, 1, v1
	v_cmp_ge_u32_e32 vcc, v3, v2
	v_add_u32_e32 v3, 1, v5
	s_nop 0
	v_cndmask_b32_e32 v1, v1, v4, vcc
	v_mul_lo_u32 v4, v2, v1
	v_add_u32_e32 v2, v4, v2
	v_cmp_ne_u32_e32 vcc, v3, v2
	s_and_saveexec_b64 s[10:11], vcc
	s_xor_b64 s[10:11], exec, s[10:11]
	s_cbranch_execz .LBB0_105
	s_waitcnt lgkmcnt(0)
	buffer_inv sc1
	s_add_u32 s18, s34, 0xed10500
	s_addc_u32 s19, s35, 0
	v_mov_b32_e32 v0, 0
	global_load_dword v0, v0, s[18:19] sc1
	s_waitcnt vmcnt(0)
	v_cmp_eq_u32_e32 vcc, v0, v1
	s_and_saveexec_b64 s[12:13], vcc
	s_cbranch_execz .LBB0_104
	s_add_u32 s16, s34, 0xed0d200
	s_addc_u32 s17, s35, 0
	s_mov_b32 s14, 1
	s_mov_b64 s[20:21], 0
	v_mov_b32_e32 v0, 0
	s_branch .LBB0_95

.LBB0_104:
	s_or_b64 exec, exec, s[12:13]
	s_waitcnt vmcnt(0)
	s_waitcnt vmcnt(0)

.LBB0_108:
	s_or_b64 exec, exec, s[12:13]
	buffer_inv sc1
	v_cvt_f32_u32_e32 v3, v0
	s_waitcnt vmcnt(0)
	v_readfirstlane_b32 s10, v2
	s_add_u32 s12, s34, 0xed10500
	s_addc_u32 s13, s35, 0
	v_rcp_iflag_f32_e32 v3, v3
	v_add_u32_e32 v1, s10, v1
	v_add_u32_e32 v4, 1, v1
	s_mov_b64 s[16:17], -1
	v_mul_f32_e32 v2, 0x4f7ffffe, v3
	v_cvt_u32_f32_e32 v2, v2
	v_sub_u32_e32 v3, 0, v0
	v_mul_lo_u32 v3, v3, v2
	v_mul_hi_u32 v3, v2, v3
	v_add_u32_e32 v2, v2, v3
	v_mul_hi_u32 v2, v1, v2
	v_mul_lo_u32 v3, v2, v0
	v_sub_u32_e32 v1, v1, v3
	v_add_u32_e32 v5, 1, v2
	v_cmp_ge_u32_e32 vcc, v1, v0
	v_sub_u32_e32 v3, v1, v0
	s_nop 0
	v_cndmask_b32_e32 v2, v2, v5, vcc
	v_cndmask_b32_e32 v1, v1, v3, vcc
	v_add_u32_e32 v3, 1, v2
	v_cmp_ge_u32_e32 vcc, v1, v0
	s_nop 1
	v_cndmask_b32_e32 v2, v2, v3, vcc
	v_mul_lo_u32 v1, v0, v2
	v_add_u32_e32 v0, v1, v0
	v_cmp_ne_u32_e32 vcc, v4, v0
	v_mov_b64_e32 v[0:1], s[12:13]
	s_and_saveexec_b64 s[10:11], vcc
	s_cbranch_execz .LBB0_120
	v_mov_b32_e32 v0, 0
	global_load_dword v1, v0, s[12:13] sc1
	s_mov_b64 s[20:21], 0
	s_waitcnt vmcnt(0)
	v_cmp_eq_u32_e32 vcc, v1, v2
	s_and_saveexec_b64 s[18:19], vcc
	s_cbranch_execz .LBB0_119
	s_add_u32 s16, s34, 0xed0d200
	s_addc_u32 s17, s35, 0
	s_mov_b32 s14, 1
	s_branch .LBB0_112

.LBB0_122:
	s_or_b64 exec, exec, s[10:11]
	s_mov_b64 s[10:11], exec
	v_mbcnt_lo_u32_b32 v0, s10, 0
	v_mbcnt_hi_u32_b32 v0, s11, v0
	v_cmp_eq_u32_e32 vcc, 0, v0
	s_and_saveexec_b64 s[12:13], vcc
	s_cbranch_execz .LBB0_124
	s_bcnt1_i32_b64 s10, s[10:11]
	v_mov_b32_e32 v0, 0x2000
	v_mov_b32_e32 v1, s10

.LBB0_1289:
	s_or_b64 exec, exec, s[10:11]
	v_cvt_f32_u32_e32 v4, v2
	s_waitcnt vmcnt(0)
	v_readfirstlane_b32 s8, v3
	v_sub_u32_e32 v3, 0, v2
	v_rcp_iflag_f32_e32 v4, v4
	v_add_u32_e32 v5, s8, v1
	v_mul_f32_e32 v4, 0x4f7ffffe, v4
	v_cvt_u32_f32_e32 v4, v4
	v_mul_lo_u32 v1, v3, v4
	v_mul_hi_u32 v1, v4, v1
	v_add_u32_e32 v1, v4, v1
	v_mul_hi_u32 v1, v5, v1
	v_mul_lo_u32 v3, v1, v2
	v_sub_u32_e32 v3, v5, v3
	v_add_u32_e32 v4, 1, v1
	v_cmp_ge_u32_e32 vcc, v3, v2
	s_nop 1
	v_cndmask_b32_e32 v1, v1, v4, vcc
	v_sub_u32_e32 v4, v3, v2
	v_cndmask_b32_e32 v3, v3, v4, vcc
	v_add_u32_e32 v4, 1, v1
	v_cmp_ge_u32_e32 vcc, v3, v2
	v_add_u32_e32 v3, 1, v5
	s_nop 0
	v_cndmask_b32_e32 v1, v1, v4, vcc
	v_mul_lo_u32 v4, v2, v1
	v_add_u32_e32 v2, v4, v2
	v_cmp_ne_u32_e32 vcc, v3, v2
	s_and_saveexec_b64 s[8:9], vcc
	s_xor_b64 s[8:9], exec, s[8:9]
	s_cbranch_execz .LBB0_1303
	s_waitcnt lgkmcnt(0)
	buffer_inv sc1
	s_add_u32 s16, s34, 0xed10500
	s_addc_u32 s17, s35, 0
	v_mov_b32_e32 v0, 0
	global_load_dword v0, v0, s[16:17] sc1
	s_waitcnt vmcnt(0)
	v_cmp_eq_u32_e32 vcc, v0, v1
	s_and_saveexec_b64 s[10:11], vcc
	s_cbranch_execz .LBB0_1302
	s_add_u32 s12, s34, 0xed0d200
	s_addc_u32 s13, s35, 0
	s_mov_b32 s14, 1
	s_mov_b64 s[18:19], 0
	v_mov_b32_e32 v0, 0
	s_branch .LBB0_1293

.LBB0_1302:
	s_or_b64 exec, exec, s[10:11]
	s_waitcnt vmcnt(0)
	s_waitcnt vmcnt(0)

.LBB0_1306:
	s_or_b64 exec, exec, s[10:11]
	buffer_inv sc1
	v_cvt_f32_u32_e32 v3, v0
	s_waitcnt vmcnt(0)
	v_readfirstlane_b32 s8, v2
	s_add_u32 s10, s34, 0xed10500
	s_addc_u32 s11, s35, 0
	v_rcp_iflag_f32_e32 v3, v3
	v_add_u32_e32 v1, s8, v1
	v_add_u32_e32 v4, 1, v1
	s_mov_b64 s[12:13], -1
	v_mul_f32_e32 v2, 0x4f7ffffe, v3
	v_cvt_u32_f32_e32 v2, v2
	v_sub_u32_e32 v3, 0, v0
	v_mul_lo_u32 v3, v3, v2
	v_mul_hi_u32 v3, v2, v3
	v_add_u32_e32 v2, v2, v3
	v_mul_hi_u32 v2, v1, v2
	v_mul_lo_u32 v3, v2, v0
	v_sub_u32_e32 v1, v1, v3
	v_add_u32_e32 v5, 1, v2
	v_cmp_ge_u32_e32 vcc, v1, v0
	v_sub_u32_e32 v3, v1, v0
	s_nop 0
	v_cndmask_b32_e32 v2, v2, v5, vcc
	v_cndmask_b32_e32 v1, v1, v3, vcc
	v_add_u32_e32 v3, 1, v2
	v_cmp_ge_u32_e32 vcc, v1, v0
	s_nop 1
	v_cndmask_b32_e32 v2, v2, v3, vcc
	v_mul_lo_u32 v1, v0, v2
	v_add_u32_e32 v0, v1, v0
	v_cmp_ne_u32_e32 vcc, v4, v0
	v_mov_b64_e32 v[0:1], s[10:11]
	s_and_saveexec_b64 s[8:9], vcc
	s_cbranch_execz .LBB0_1318
	v_mov_b32_e32 v0, 0
	global_load_dword v1, v0, s[10:11] sc1
	s_mov_b64 s[18:19], 0
	s_waitcnt vmcnt(0)
	v_cmp_eq_u32_e32 vcc, v1, v2
	s_and_saveexec_b64 s[16:17], vcc
	s_cbranch_execz .LBB0_1317
	s_add_u32 s12, s34, 0xed0d200
	s_addc_u32 s13, s35, 0
	s_mov_b32 s14, 1
	s_branch .LBB0_1310

.LBB0_1320:
	s_or_b64 exec, exec, s[8:9]
	s_mov_b64 s[8:9], exec
	v_mbcnt_lo_u32_b32 v0, s8, 0
	v_mbcnt_hi_u32_b32 v0, s9, v0
	v_cmp_eq_u32_e32 vcc, 0, v0
	s_and_saveexec_b64 s[10:11], vcc
	s_cbranch_execz .LBB0_1322
	s_bcnt1_i32_b64 s8, s[8:9]
	v_mov_b32_e32 v0, 0x2000
	v_mov_b32_e32 v1, s8

.LBB0_1533:
	s_or_b64 exec, exec, s[12:13]
	v_cvt_f32_u32_e32 v4, v2
	s_waitcnt vmcnt(0)
	v_readfirstlane_b32 s3, v3
	v_sub_u32_e32 v3, 0, v2
	v_rcp_iflag_f32_e32 v4, v4
	v_add_u32_e32 v5, s3, v1
	v_mul_f32_e32 v4, 0x4f7ffffe, v4
	v_cvt_u32_f32_e32 v4, v4
	v_mul_lo_u32 v1, v3, v4
	v_mul_hi_u32 v1, v4, v1
	v_add_u32_e32 v1, v4, v1
	v_mul_hi_u32 v1, v5, v1
	v_mul_lo_u32 v3, v1, v2
	v_sub_u32_e32 v3, v5, v3
	v_add_u32_e32 v4, 1, v1
	v_cmp_ge_u32_e32 vcc, v3, v2
	s_nop 1
	v_cndmask_b32_e32 v1, v1, v4, vcc
	v_sub_u32_e32 v4, v3, v2
	v_cndmask_b32_e32 v3, v3, v4, vcc
	v_add_u32_e32 v4, 1, v1
	v_cmp_ge_u32_e32 vcc, v3, v2
	v_add_u32_e32 v3, 1, v5
	s_nop 0
	v_cndmask_b32_e32 v1, v1, v4, vcc
	v_mul_lo_u32 v4, v2, v1
	v_add_u32_e32 v2, v4, v2
	v_cmp_ne_u32_e32 vcc, v3, v2
	s_and_saveexec_b64 s[10:11], vcc
	s_xor_b64 s[10:11], exec, s[10:11]
	s_cbranch_execz .LBB0_1547
	s_waitcnt lgkmcnt(0)
	buffer_inv sc1
	s_add_u32 s16, s34, 0xed10500
	s_addc_u32 s17, s35, 0
	v_mov_b32_e32 v0, 0
	global_load_dword v0, v0, s[16:17] sc1
	s_waitcnt vmcnt(0)
	v_cmp_eq_u32_e32 vcc, v0, v1
	s_and_saveexec_b64 s[12:13], vcc
	s_cbranch_execz .LBB0_1546
	s_add_u32 s14, s34, 0xed0d200
	s_addc_u32 s15, s35, 0
	s_mov_b32 s3, 1
	s_mov_b64 s[18:19], 0
	v_mov_b32_e32 v0, 0
	s_branch .LBB0_1537

.LBB0_1550:
	s_or_b64 exec, exec, s[12:13]
	buffer_inv sc1
	v_cvt_f32_u32_e32 v3, v0
	s_waitcnt vmcnt(0)
	v_readfirstlane_b32 s3, v2
	s_add_u32 s12, s34, 0xed10500
	s_addc_u32 s13, s35, 0
	v_rcp_iflag_f32_e32 v3, v3
	v_add_u32_e32 v1, s3, v1
	v_add_u32_e32 v4, 1, v1
	s_mov_b64 s[14:15], -1
	v_mul_f32_e32 v2, 0x4f7ffffe, v3
	v_cvt_u32_f32_e32 v2, v2
	v_sub_u32_e32 v3, 0, v0
	v_mul_lo_u32 v3, v3, v2
	v_mul_hi_u32 v3, v2, v3
	v_add_u32_e32 v2, v2, v3
	v_mul_hi_u32 v2, v1, v2
	v_mul_lo_u32 v3, v2, v0
	v_sub_u32_e32 v1, v1, v3
	v_add_u32_e32 v5, 1, v2
	v_cmp_ge_u32_e32 vcc, v1, v0
	v_sub_u32_e32 v3, v1, v0
	s_nop 0
	v_cndmask_b32_e32 v2, v2, v5, vcc
	v_cndmask_b32_e32 v1, v1, v3, vcc
	v_add_u32_e32 v3, 1, v2
	v_cmp_ge_u32_e32 vcc, v1, v0
	s_nop 1
	v_cndmask_b32_e32 v2, v2, v3, vcc
	v_mul_lo_u32 v1, v0, v2
	v_add_u32_e32 v0, v1, v0
	v_cmp_ne_u32_e32 vcc, v4, v0
	v_mov_b64_e32 v[0:1], s[12:13]
	s_and_saveexec_b64 s[10:11], vcc
	s_cbranch_execz .LBB0_1562
	v_mov_b32_e32 v0, 0
	global_load_dword v1, v0, s[12:13] sc1
	s_mov_b64 s[18:19], 0
	s_waitcnt vmcnt(0)
	v_cmp_eq_u32_e32 vcc, v1, v2
	s_and_saveexec_b64 s[16:17], vcc
	s_cbranch_execz .LBB0_1561
	s_add_u32 s14, s34, 0xed0d200
	s_addc_u32 s15, s35, 0
	s_mov_b32 s3, 1
	s_branch .LBB0_1554

.LBB0_1564:
	s_or_b64 exec, exec, s[10:11]
	s_mov_b64 s[10:11], exec
	v_mbcnt_lo_u32_b32 v0, s10, 0
	v_mbcnt_hi_u32_b32 v0, s11, v0
	v_cmp_eq_u32_e32 vcc, 0, v0
	s_and_saveexec_b64 s[12:13], vcc
	s_cbranch_execz .LBB0_1566
	s_bcnt1_i32_b64 s3, s[10:11]
	v_mov_b32_e32 v0, 0x2000
	v_mov_b32_e32 v1, s3
